# P1 GEMM: LDS-DMA pieces re-cut to 8 rows x 128 B full lines (new XOR-swizzled LDS image, alt base regs for k=1 fragments), on top of attention setprio
# baseline (speedup 1.0000x reference)
; #define PG8_STAGE(bufoff, gbase, voff) do { _Pragma("unroll") for (int _i = 0; _i < 2; ++_i) \
;         __builtin_amdgcn_global_load_lds((const unsigned*)((const char*)(gbase) + (voff)[_i]), (PG8_LAS unsigned*)(lds + (bufoff) + ldsw + _i * 8192), 16, 0, 0); } while (0)
; #define PG8_BAR __builtin_amdgcn_s_barrier()
; template <class Epi, class Sched, bool ALIGN_EPI = false, bool SP2 = false>
; __device__ __forceinline__ void gemm_phase(PG8_LAS unsigned char* lds, const Gemm g, const Sched& S, const Epi& E) {
;     ...
;     for (int i = 0; i < 2; ++i) { int R, C; stage_rc(tid * 16 + i * 8192, R, C); const int Rb = Epi::PERM ? ((R & ~31) + perm32(R & 31)) : R;
;         voffA[i] = (unsigned)(R * K + C) * 2u; voffB[i] = (unsigned)(Rb * K + C) * 2u; }
;     const size_t kstep = (size_t)(BK * 2);
;     const size_t hstep = (size_t)HALF * K * 2;
;     const size_t tstep = 2 * hstep;
;     const unsigned ldsw = (unsigned)wid * 1024u;
;     const int aoff = lds_byte(wr * 64 + fr, fq * 8), boff = lds_byte(wc * 32 + fr, fq * 8);
;     ...
;     const char* cA = (const char*)g.A + (size_t)cur.pm * tstep; const char* cB = (const char*)g.Bt + (size_t)cur.pn * tstep;
;     S.a_ready(cur);
;     if constexpr (SP2) {
;         PG8_STAGE(PG8_SB(0, 0), cB, voffB); PG8_STAGE(PG8_SB(0, 1), cB + hstep, voffB); PG8_STAGE(PG8_SA(0, 0), cA, voffA); PG8_STAGE(PG8_SA(0, 1), cA + hstep, voffA);
;         if (wr == 1) PG8_BAR;
.LBB0_90:
	s_or_b64 exec, exec, s[4:5]
	s_mov_b64 s[4:5], s[0:1]
	v_mov_b32_e32 v8, v164
	s_cmpk_gt_i32 s2, 0xbff
	v_readfirstlane_b32 s18, v8
	s_cbranch_scc1 .LBB0_106
	v_lshlrev_b32_e32 v0, 4, v8
	v_add_u32_e32 v1, 0x2000, v0
	v_ashrrev_i32_e32 v2, 31, v1
	v_lshrrev_b32_e32 v2, 22, v2
	v_add_u32_e32 v2, v1, v2
	v_ashrrev_i32_e32 v9, 10, v2
	v_mul_i32_i24_e32 v2, 0x400, v9
	v_sub_u32_e32 v1, v1, v2
	v_lshrrev_b32_e32 v2, 4, v1
	v_bitop3_b32 v1, v2, v1, 32 bitop3:0x6c
	v_ashrrev_i32_e32 v2, 31, v1
	v_lshrrev_b32_e32 v2, 26, v2
	v_add_u32_e32 v2, v1, v2
	v_lshlrev_b32_e32 v3, 3, v9
	v_ashrrev_i32_e32 v10, 6, v2
	v_and_b32_e32 v3, -16, v3
	v_add_u32_e32 v3, v10, v3
	s_load_dwordx4 s[8:11], s[4:5], 0x90
	v_and_b32_e32 v4, 3, v10
	s_mov_b32 s4, 0xfffe0
	v_lshrrev_b32_e32 v5, 2, v3
	v_lshlrev_b32_e32 v6, 1, v3
	v_and_b32_e32 v2, 0xc0, v2
	v_and_or_b32 v4, v3, s4, v4
	v_and_b32_e32 v5, 4, v5
	v_and_b32_e32 v6, 24, v6
	v_sub_u32_e32 v1, v1, v2
	v_mov_b32_e32 v2, 1
	v_or3_b32 v4, v4, v5, v6
	v_lshlrev_b32_e32 v5, 5, v9
	v_ashrrev_i16_sdwa v1, v2, sext(v1) dst_sel:DWORD dst_unused:UNUSED_PAD src0_sel:DWORD src1_sel:BYTE_0
	v_and_b32_e32 v5, 32, v5
	v_bfe_i32 v11, v1, 0, 16
	v_add_lshl_u32 v1, v5, v11, 1
	v_lshrrev_b32_e32 v240, 3, v8
	v_lshrrev_b32_e32 v241, 4, v8
	v_xor_b32_e32 v241, v241, v8
	v_and_b32_e32 v241, 7, v241
	v_lshlrev_b32_e32 v241, 4, v241
	v_bfe_u32 v242, v240, 2, 3
	v_lshlrev_b32_e32 v243, 1, v242
	v_lshrrev_b32_e32 v244, 2, v242
	v_and_or_b32 v243, v243, 7, v244
	v_and_b32_e32 v245, 35, v240
	v_lshl_or_b32 v245, v243, 2, v245
	v_lshl_add_u32 v246, v240, 12, v241
	v_lshl_add_u32 v247, v245, 12, v241
	v_add_u32_e32 v132, 0x40000, v246
	v_add_u32_e32 v130, 0x40000, v247
	v_bfe_i32 v1, v8, 27, 1
	v_lshrrev_b32_e32 v1, 22, v1
	v_add_u32_e32 v1, v0, v1
	v_and_b32_e32 v1, 0xfffffc00, v1
	v_sub_u32_e32 v0, v0, v1
	v_lshrrev_b32_e32 v1, 4, v0
	v_ashrrev_i32_e32 v3, 31, v8
	v_bitop3_b32 v0, v1, v0, 32 bitop3:0x6c
	v_lshrrev_b32_e32 v3, 26, v3
	v_ashrrev_i32_e32 v1, 31, v0
	v_add_u32_e32 v3, v8, v3
	v_lshrrev_b32_e32 v1, 26, v1
	v_ashrrev_i32_e32 v13, 6, v3
	v_add_u32_e32 v1, v0, v1
	v_lshlrev_b32_e32 v3, 3, v13
	s_waitcnt lgkmcnt(0)
	s_add_u32 s21, s10, 0x500000
	v_ashrrev_i32_e32 v12, 6, v1
	v_and_b32_e32 v3, -16, v3
	s_addc_u32 s23, s11, 0
	v_add_u32_e32 v3, v12, v3
	v_and_b32_e32 v4, 3, v12
	s_ashr_i32 s51, s2, 31
	v_and_or_b32 v4, v3, s4, v4
	s_lshr_b32 s4, s51, 29
	s_add_i32 s4, s2, s4
	s_ashr_i32 s19, s18, 6
	s_ashr_i32 s6, s4, 3
	s_and_b32 s4, s4, -8
	s_ashr_i32 s5, s18, 8
	s_lshl_b32 s50, s19, 10
	s_sub_i32 s4, s2, s4
	s_cmp_lt_i32 s4, 0
	s_movk_i32 s52, 0x181
	s_cselect_b32 s7, s52, 0x180
	s_mul_i32 s4, s4, s7
	s_add_i32 s4, s4, s6
	s_mul_hi_i32 s6, s4, 0x2aaaaaab
	s_lshr_b32 s7, s6, 31
	s_ashr_i32 s6, s6, 4
	s_add_i32 s6, s6, s7
	s_lshl_b32 s7, s6, 2
	s_mulk_i32 s6, 0x60
	s_sub_i32 s6, s4, s6
	s_bfe_i32 s4, s6, 0x80000
	s_bfe_u32 s4, s4, 0x2000d
	s_add_i32 s12, s6, s4
	s_bfe_i32 s4, s12, 0x80000
	s_and_b32 s12, s12, 0xfc
	s_sub_i32 s6, s6, s12
	s_sext_i32_i16 s4, s4
	s_sext_i32_i8 s6, s6
	v_lshrrev_b32_e32 v5, 2, v3
	v_lshlrev_b32_e32 v6, 1, v3
	v_and_b32_e32 v1, 0xc0, v1
	s_lshr_b32 s4, s4, 2
	s_add_i32 s44, s7, s6
	v_and_b32_e32 v5, 4, v5
	v_and_b32_e32 v6, 24, v6
	v_sub_u32_e32 v0, v0, v1
	s_ashr_i32 s45, s44, 31
	s_bfe_i64 s[12:13], s[4:5], 0x100000
	v_or3_b32 v4, v4, v5, v6
	v_lshlrev_b32_e32 v5, 5, v13
	v_ashrrev_i16_sdwa v0, v2, sext(v0) dst_sel:DWORD dst_unused:UNUSED_PAD src0_sel:DWORD src1_sel:BYTE_0
	s_lshl_b64 s[6:7], s[44:45], 20
	s_lshl_b64 s[12:13], s[12:13], 20
	v_and_b32_e32 v5, 32, v5
	v_bfe_i32 v14, v0, 0, 16
	s_add_u32 s46, s21, s12
	v_add_lshl_u32 v0, v5, v14, 1
	s_addc_u32 s47, s23, s13
	s_add_i32 s45, s50, 0
	v_mov_b32_e32 v134, v247
	s_add_i32 m0, s45, 0x10000
	v_mov_b32_e32 v136, v246
	global_load_lds_dwordx4 v134, s[46:47]
	s_add_i32 m0, s45, 0x12000
	s_add_u32 s12, s46, 0x80000
	global_load_lds_dwordx4 v130, s[46:47]
	s_addc_u32 s13, s47, 0
	s_add_i32 m0, s45, 0x14000
	v_mov_b32_e32 v135, 0
	global_load_lds_dwordx4 v134, s[12:13]
	s_add_i32 m0, s45, 0x16000
	s_add_u32 s6, s8, s6
	s_addc_u32 s7, s9, s7
	s_add_i32 s53, s45, 0x2000
	global_load_lds_dwordx4 v130, s[12:13]
	s_mov_b32 m0, s45
	s_add_u32 s12, s6, 0x80000
	global_load_lds_dwordx4 v136, s[6:7]
	s_mov_b32 m0, s53
	s_addc_u32 s13, s7, 0
	s_add_i32 s54, s45, 0x4000
	global_load_lds_dwordx4 v132, s[6:7]
	s_mov_b32 m0, s54
	s_add_i32 s55, s45, 0x6000
	global_load_lds_dwordx4 v136, s[12:13]
	s_mov_b32 m0, s55
	v_mov_b32_e32 v131, v135
	global_load_lds_dwordx4 v132, s[12:13]
	v_mov_b32_e32 v137, v135
	v_mov_b32_e32 v133, v135
	s_cmp_eq_u32 s5, 1
	s_mov_b32 s56, 0
	v_lshl_add_u64 v[6:7], s[46:47], 0, v[134:135]
	v_lshl_add_u64 v[2:3], s[46:47], 0, v[130:131]
	s_mov_b64 s[12:13], 0x80000
	v_lshl_add_u64 v[0:1], s[6:7], 0, v[136:137]
	s_cselect_b64 s[16:17], -1, 0
	s_cmp_lg_u32 s5, 1
	v_lshl_add_u64 v[4:5], s[6:7], 0, v[132:133]
	s_cbranch_scc1 .LBB0_93
	s_barrier
; #define PG8_STAGE(bufoff, gbase, voff) do { _Pragma("unroll") for (int _i = 0; _i < 2; ++_i) \
;         __builtin_amdgcn_global_load_lds((const unsigned*)((const char*)(gbase) + (voff)[_i]), (PG8_LAS unsigned*)(lds + (bufoff) + ldsw + _i * 8192), 16, 0, 0); } while (0)
; #define PG8_WAIT_V(n) asm volatile("s_waitcnt vmcnt(" #n ")" ::: "memory")
; #define PG8_BAR __builtin_amdgcn_s_barrier()
; template <class Epi, class Sched, bool ALIGN_EPI = false, bool SP2 = false>
; __device__ __forceinline__ void gemm_phase(PG8_LAS unsigned char* lds, const Gemm g, const Sched& S, const Epi& E) {
;     ...
;     for (int i = 0; i < 2; ++i) { int R, C; stage_rc(tid * 16 + i * 8192, R, C); const int Rb = Epi::PERM ? ((R & ~31) + perm32(R & 31)) : R;
;         voffA[i] = (unsigned)(R * K + C) * 2u; voffB[i] = (unsigned)(Rb * K + C) * 2u; }
;     const size_t kstep = (size_t)(BK * 2);
;     const size_t hstep = (size_t)HALF * K * 2;
;     const size_t tstep = 2 * hstep;
;     const unsigned ldsw = (unsigned)wid * 1024u;
;     const int aoff = lds_byte(wr * 64 + fr, fq * 8), boff = lds_byte(wc * 32 + fr, fq * 8);
;     ...
;         PG8_WAIT_V(2); PG8_BAR;
;         PG8_STAGE(PG8_SB(1, 0), cB + kstep, voffB); PG8_STAGE(PG8_SA(1, 0), cA + kstep, voffA); PG8_STAGE(PG8_SB(1, 1), cB + hstep + kstep, voffB);
;         PG8_WAIT_V(6); PG8_BAR;
.LBB0_93:
	s_add_u32 s57, s10, 0x6600000
	s_addc_u32 s58, s11, 0
	s_lshl_b32 s10, s19, 5
	s_and_b32 s31, s10, 0x60
	s_mov_b64 s[10:11], 0x80
	s_add_i32 m0, s45, 0x18000
	v_lshl_add_u64 v[6:7], v[6:7], 0, s[10:11]
	s_lshl_b32 s30, s5, 13
	s_lshl_b32 s19, s31, 7
	s_waitcnt vmcnt(2)
	s_barrier
	global_load_lds_dwordx4 v[6:7], off
	v_lshl_add_u64 v[2:3], v[2:3], 0, s[10:11]
	s_add_i32 m0, s45, 0x1a000
	s_add_i32 s59, s45, 0x8000
	s_add_i32 s60, s45, 0xa000
	global_load_lds_dwordx4 v[2:3], off
	v_lshl_add_u64 v[0:1], v[0:1], 0, s[10:11]
	s_mov_b32 m0, s59
	s_add_u32 s28, s46, 0x80080
	global_load_lds_dwordx4 v[0:1], off
	v_lshl_add_u64 v[0:1], v[4:5], 0, s[10:11]
	s_mov_b32 m0, s60
	s_addc_u32 s29, s47, 0
	global_load_lds_dwordx4 v[0:1], off
	s_add_i32 m0, s45, 0x1c000
	v_lshl_add_u64 v[0:1], s[28:29], 0, v[134:135]
	global_load_lds_dwordx4 v[0:1], off
	v_lshl_add_u64 v[0:1], s[28:29], 0, v[130:131]
	s_add_i32 m0, s45, 0x1e000
	s_cmpk_lt_u32 s18, 0x100
	global_load_lds_dwordx4 v[0:1], off
	v_lshrrev_b32_e32 v1, 1, v8
	v_and_b32_e32 v1, 24, v1
	v_and_b32_e32 v0, 15, v8
	v_lshlrev_b32_e32 v2, 1, v1
	v_lshl_or_b32 v147, s5, 6, v0
	v_lshl_or_b32 v0, v0, 6, v2
	v_lshlrev_b32_e32 v2, 2, v8
	v_and_b32_e32 v2, 32, v2
	v_bitop3_b32 v3, v0, s30, v2 bitop3:0xde
	v_bitop3_b32 v150, v0, s19, v2 bitop3:0xde
	v_lshlrev_b32_e32 v0, 15, v13
	v_and_b32_e32 v0, 0xffff0000, v0
	v_or_b32_e32 v151, s31, v1
	v_lshl_add_u32 v0, v12, 12, v0
	v_and_b32_e32 v1, 1, v13
	v_lshl_or_b32 v0, v1, 6, v0
	v_lshl_add_u32 v138, v14, 1, v0
	v_lshlrev_b32_e32 v0, 15, v9
	v_and_b32_e32 v0, 0xffff0000, v0
	s_waitcnt vmcnt(6)
	v_lshl_add_u32 v0, v10, 12, v0
	v_and_b32_e32 v1, 1, v9
	s_cselect_b64 s[18:19], -1, 0
	v_lshl_or_b32 v0, v1, 6, v0
	s_add_i32 s63, 0, 0x10000
	s_add_i32 s64, 0, 0x14000
	s_sext_i32_i8 s69, s4
	s_ashr_i32 s61, s24, 31
	s_mov_b32 s62, s24
	v_mov_b32_e32 v139, v135
	v_lshl_add_u32 v140, v11, 1, v0
	v_mov_b32_e32 v141, v135
	v_mov_b32_e32 v138, v246
	v_mov_b32_e32 v140, v132
	v_mov_b64_e32 v[142:143], 0xc00
	v_mov_b64_e32 v[144:145], 0xbff
	v_add_u32_e32 v152, s63, v150
	v_add_u32_e32 v153, s64, v150
	v_add_u32_e32 v154, 0, v3
	v_and_b32_e32 v248, 15, v164
	v_bfe_u32 v249, v164, 4, 2
	v_bfe_u32 v250, v248, 1, 3
	v_xor_b32_e32 v249, v249, v250
	v_lshlrev_b32_e32 v249, 4, v249
	v_and_b32_e32 v250, 7, v248
	v_lshl_or_b32 v249, v250, 7, v249
	v_lshrrev_b32_e32 v250, 3, v248
	v_lshl_or_b32 v249, v250, 10, v249
	v_mov_b32_e32 v250, 0xfffff000
	v_and_or_b32 v150, v150, v250, v249
	v_xor_b32_e32 v234, 64, v150
	v_and_or_b32 v152, v152, v250, v249
	v_xor_b32_e32 v235, 64, v152
	v_and_or_b32 v153, v153, v250, v249
	v_xor_b32_e32 v236, 64, v153
	v_and_or_b32 v154, v154, v250, v249
	v_xor_b32_e32 v237, 64, v154
	s_mov_b32 s65, 0x80000
	s_mov_b64 s[28:29], 0x90000
	s_mov_b32 s66, 0x90000
	s_mov_b64 s[30:31], 0xa0000
	s_mov_b32 s67, 0xa0000
	s_mov_b64 s[34:35], 0xb0000
	s_mov_b32 s68, 0xb0000
	v_mov_b32_e32 v155, 0x3e0293ee
	v_mov_b32_e32 v156, 0x3e38aa3b
	s_barrier
	s_branch .LBB0_96

; #define PG8_STAGE(bufoff, gbase, voff) do { _Pragma("unroll") for (int _i = 0; _i < 2; ++_i) \
;         __builtin_amdgcn_global_load_lds((const unsigned*)((const char*)(gbase) + (voff)[_i]), (PG8_LAS unsigned*)(lds + (bufoff) + ldsw + _i * 8192), 16, 0, 0); } while (0)
; #define PG8_LDA(dst, b, h) do { _Pragma("unroll") for (int m = 0; m < 4; ++m) _Pragma("unroll") for (int k = 0; k < 2; ++k) dst[m][k] = *(const PG8_LAS bf16x8*)(lds + PG8_SA(b, h) + aoff + m * 2048 + k * 1024); } while (0)
; #define PG8_LDB(dst, b, h) do { _Pragma("unroll") for (int n = 0; n < 2; ++n) _Pragma("unroll") for (int k = 0; k < 2; ++k) dst[n][k] = *(const PG8_LAS bf16x8*)(lds + PG8_SB(b, h) + boff + n * 2048 + k * 1024); } while (0)
; #define PG8_MMA(ai, bj, At, Bt) do { __builtin_amdgcn_s_setprio(1); _Pragma("unroll") for (int m = 0; m < 4; ++m) _Pragma("unroll") for (int n = 0; n < 2; ++n) _Pragma("unroll") for (int k = 0; k < 2; ++k) \
;         acc[ai][bj][m][n] = __builtin_amdgcn_mfma_f32_16x16x32_bf16(Bt[n][k], At[m][k], acc[ai][bj][m][n], 0, 0, 0); __builtin_amdgcn_s_setprio(0); } while (0)
; #define PG8_WAIT_V(n) asm volatile("s_waitcnt vmcnt(" #n ")" ::: "memory")
; #define PG8_WAIT_L(n) asm volatile("s_waitcnt lgkmcnt(" #n ")" ::: "memory")
; #define PG8_BAR __builtin_amdgcn_s_barrier()
; #define PG8_SCHED __builtin_amdgcn_sched_barrier(0)
; template <class Epi, class Sched, bool ALIGN_EPI = false, bool SP2 = false>
; __device__ __forceinline__ void gemm_phase(PG8_LAS unsigned char* lds, const Gemm g, const Sched& S, const Epi& E) {
;     ...
;             const char* a2 = last ? nA : cA + (size_t)(t + 2) * kstep; const char* b2 = last ? nB : cB + (size_t)(t + 2) * kstep;
;             const char* a3 = a2 + kstep; const char* b3 = b2 + kstep;
;             if (last && has_next) S.a_ready(nxt);
;             if constexpr (SP2) {
;             PG8_LDB(B0, 0, 0); PG8_LDB(B1, 0, 1); PG8_SCHED; PG8_LDA(At, 0, 0); PG8_STAGE(PG8_SA(1, 1), a1 + hstep, voffA);
;             PG8_WAIT_V(8); PG8_WAIT_L(0); PG8_BAR; PG8_MMA(0, 0, At, B0); PG8_MMA(0, 1, At, B1); PG8_BAR; PG8_SCHED;
;             PG8_LDA(At, 0, 1); PG8_STAGE(PG8_SB(0, 0), b2, voffB); PG8_STAGE(PG8_SB(0, 1), b2 + hstep, voffB); PG8_STAGE(PG8_SA(0, 0), a2, voffA);
;             PG8_WAIT_V(8); PG8_WAIT_L(0); PG8_BAR; PG8_MMA(1, 0, At, B0); PG8_MMA(1, 1, At, B1); PG8_BAR; PG8_SCHED;
.LBB0_99:
	ds_read_b128 v[158:161], v152
	ds_read_b128 v[168:171], v235
	ds_read_b128 v[172:175], v152 offset:2048
	ds_read_b128 v[176:179], v235 offset:2048
	ds_read_b128 v[180:183], v153
	ds_read_b128 v[184:187], v236
	ds_read_b128 v[188:191], v153 offset:2048
	ds_read_b128 v[192:195], v236 offset:2048
	s_add_u32 s46, s6, 0xfff80080
	s_addc_u32 s47, s7, -1
	s_cmp_eq_u32 s74, 28
	s_cselect_b32 s49, s39, s47
	s_cselect_b32 s48, s70, s46
	s_cselect_b32 s47, s37, s73
	s_cselect_b32 s46, s71, s72
	v_lshl_add_u64 v[148:149], s[6:7], 0, v[138:139]
	s_add_i32 m0, s45, 0xc000
	ds_read_b128 v[196:199], v154
	ds_read_b128 v[200:203], v237
	ds_read_b128 v[204:207], v154 offset:2048
	ds_read_b128 v[208:211], v237 offset:2048
	ds_read_b128 v[212:215], v154 offset:4096
	ds_read_b128 v[216:219], v237 offset:4096
	ds_read_b128 v[220:223], v154 offset:6144
	ds_read_b128 v[224:227], v237 offset:6144
	global_load_lds_dwordx4 v[148:149], off
	v_lshl_add_u64 v[148:149], s[6:7], 0, v[140:141]
	s_add_i32 m0, s45, 0xe000
	s_nop 0
	global_load_lds_dwordx4 v[148:149], off
	s_waitcnt vmcnt(8)
	s_waitcnt lgkmcnt(0)
	s_barrier
	s_setprio 1
	s_waitcnt lgkmcnt(0)
	v_mfma_f32_16x16x32_bf16 v[124:127], v[158:161], v[196:199], v[124:127]
	v_mfma_f32_16x16x32_bf16 v[120:123], v[172:175], v[196:199], v[120:123]
	v_mfma_f32_16x16x32_bf16 v[108:111], v[158:161], v[204:207], v[108:111]
	v_mfma_f32_16x16x32_bf16 v[104:107], v[172:175], v[204:207], v[104:107]
	v_mfma_f32_16x16x32_bf16 v[92:95], v[158:161], v[212:215], v[92:95]
	v_mfma_f32_16x16x32_bf16 v[88:91], v[172:175], v[212:215], v[88:91]
	v_mfma_f32_16x16x32_bf16 v[76:79], v[158:161], v[220:223], v[76:79]
	v_mfma_f32_16x16x32_bf16 v[72:75], v[172:175], v[220:223], v[72:75]
	v_mfma_f32_16x16x32_bf16 v[124:127], v[168:171], v[200:203], v[124:127]
	v_mfma_f32_16x16x32_bf16 v[120:123], v[176:179], v[200:203], v[120:123]
	v_mfma_f32_16x16x32_bf16 v[108:111], v[168:171], v[208:211], v[108:111]
	v_mfma_f32_16x16x32_bf16 v[104:107], v[176:179], v[208:211], v[104:107]
	v_mfma_f32_16x16x32_bf16 v[92:95], v[168:171], v[216:219], v[92:95]
	v_mfma_f32_16x16x32_bf16 v[88:91], v[176:179], v[216:219], v[88:91]
	v_mfma_f32_16x16x32_bf16 v[76:79], v[168:171], v[224:227], v[76:79]
	v_mfma_f32_16x16x32_bf16 v[72:75], v[176:179], v[224:227], v[72:75]
	s_setprio 0
	s_setprio 1
	v_mfma_f32_16x16x32_bf16 v[116:119], v[180:183], v[196:199], v[116:119]
	v_mfma_f32_16x16x32_bf16 v[112:115], v[188:191], v[196:199], v[112:115]
	v_mfma_f32_16x16x32_bf16 v[100:103], v[180:183], v[204:207], v[100:103]
	v_mfma_f32_16x16x32_bf16 v[96:99], v[188:191], v[204:207], v[96:99]
	v_mfma_f32_16x16x32_bf16 v[84:87], v[180:183], v[212:215], v[84:87]
	v_mfma_f32_16x16x32_bf16 v[80:83], v[188:191], v[212:215], v[80:83]
	v_mfma_f32_16x16x32_bf16 v[68:71], v[180:183], v[220:223], v[68:71]
	v_mfma_f32_16x16x32_bf16 v[64:67], v[188:191], v[220:223], v[64:67]
	v_mfma_f32_16x16x32_bf16 v[116:119], v[184:187], v[200:203], v[116:119]
	v_mfma_f32_16x16x32_bf16 v[112:115], v[192:195], v[200:203], v[112:115]
	v_mfma_f32_16x16x32_bf16 v[100:103], v[184:187], v[208:211], v[100:103]
	v_mfma_f32_16x16x32_bf16 v[96:99], v[192:195], v[208:211], v[96:99]
	v_mfma_f32_16x16x32_bf16 v[84:87], v[184:187], v[216:219], v[84:87]
	v_mfma_f32_16x16x32_bf16 v[80:83], v[192:195], v[216:219], v[80:83]
	v_mfma_f32_16x16x32_bf16 v[68:71], v[184:187], v[224:227], v[68:71]
	v_mfma_f32_16x16x32_bf16 v[64:67], v[192:195], v[224:227], v[64:67]
	s_setprio 0
	s_barrier
	s_add_i32 s75, s63, s50
	v_lshl_add_u64 v[148:149], s[46:47], 0, v[134:135]
	s_mov_b32 m0, s75
	ds_read_b128 v[196:199], v154 offset:16384
	ds_read_b128 v[200:203], v237 offset:16384
	ds_read_b128 v[204:207], v154 offset:18432
	ds_read_b128 v[208:211], v237 offset:18432
	ds_read_b128 v[212:215], v154 offset:20480
	ds_read_b128 v[216:219], v237 offset:20480
	ds_read_b128 v[220:223], v154 offset:22528
	ds_read_b128 v[224:227], v237 offset:22528
	global_load_lds_dwordx4 v[148:149], off
	s_add_i32 m0, s75, 0x2000
	s_add_u32 s76, s46, 0x80000
	v_lshl_add_u64 v[162:163], s[46:47], 0, v[130:131]
	s_addc_u32 s77, s47, 0
	s_add_i32 s75, s64, s50
	global_load_lds_dwordx4 v[162:163], off
	v_lshl_add_u64 v[228:229], s[76:77], 0, v[134:135]
	s_mov_b32 m0, s75
	v_lshl_add_u64 v[230:231], s[48:49], 0, v[132:133]
	global_load_lds_dwordx4 v[228:229], off
	v_lshl_add_u64 v[228:229], s[76:77], 0, v[130:131]
	s_add_i32 m0, s75, 0x2000
	s_nop 0
	global_load_lds_dwordx4 v[228:229], off
	v_lshl_add_u64 v[228:229], s[48:49], 0, v[136:137]
	s_mov_b32 m0, s45
	s_nop 0
	global_load_lds_dwordx4 v[228:229], off
	s_mov_b32 m0, s53
	s_nop 0
	global_load_lds_dwordx4 v[230:231], off
	s_waitcnt vmcnt(8)
	s_waitcnt lgkmcnt(0)
	s_barrier
; #define PG8_STAGE(bufoff, gbase, voff) do { _Pragma("unroll") for (int _i = 0; _i < 2; ++_i) \
;         __builtin_amdgcn_global_load_lds((const unsigned*)((const char*)(gbase) + (voff)[_i]), (PG8_LAS unsigned*)(lds + (bufoff) + ldsw + _i * 8192), 16, 0, 0); } while (0)
; #define PG8_LDA(dst, b, h) do { _Pragma("unroll") for (int m = 0; m < 4; ++m) _Pragma("unroll") for (int k = 0; k < 2; ++k) dst[m][k] = *(const PG8_LAS bf16x8*)(lds + PG8_SA(b, h) + aoff + m * 2048 + k * 1024); } while (0)
; #define PG8_LDB(dst, b, h) do { _Pragma("unroll") for (int n = 0; n < 2; ++n) _Pragma("unroll") for (int k = 0; k < 2; ++k) dst[n][k] = *(const PG8_LAS bf16x8*)(lds + PG8_SB(b, h) + boff + n * 2048 + k * 1024); } while (0)
; #define PG8_MMA(ai, bj, At, Bt) do { __builtin_amdgcn_s_setprio(1); _Pragma("unroll") for (int m = 0; m < 4; ++m) _Pragma("unroll") for (int n = 0; n < 2; ++n) _Pragma("unroll") for (int k = 0; k < 2; ++k) \
;         acc[ai][bj][m][n] = __builtin_amdgcn_mfma_f32_16x16x32_bf16(Bt[n][k], At[m][k], acc[ai][bj][m][n], 0, 0, 0); __builtin_amdgcn_s_setprio(0); } while (0)
; #define PG8_WAIT_V(n) asm volatile("s_waitcnt vmcnt(" #n ")" ::: "memory")
; #define PG8_WAIT_L(n) asm volatile("s_waitcnt lgkmcnt(" #n ")" ::: "memory")
; #define PG8_BAR __builtin_amdgcn_s_barrier()
; #define PG8_SCHED __builtin_amdgcn_sched_barrier(0)
; template <class Epi, class Sched, bool ALIGN_EPI = false, bool SP2 = false>
; __device__ __forceinline__ void gemm_phase(PG8_LAS unsigned char* lds, const Gemm g, const Sched& S, const Epi& E) {
;     ...
;             PG8_WAIT_V(8); PG8_WAIT_L(0); PG8_BAR; PG8_MMA(1, 0, At, B0); PG8_MMA(1, 1, At, B1); PG8_BAR; PG8_SCHED;
;             PG8_LDB(B0, 1, 0); PG8_LDB(B1, 1, 1); PG8_SCHED; PG8_LDA(At, 1, 0); PG8_STAGE(PG8_SA(0, 1), a2 + hstep, voffA);
;             PG8_WAIT_V(8); PG8_WAIT_L(0); PG8_BAR; PG8_MMA(0, 0, At, B0); PG8_MMA(0, 1, At, B1); PG8_BAR; PG8_SCHED;
	s_setprio 1
	s_waitcnt lgkmcnt(0)
	v_mfma_f32_16x16x32_bf16 v[60:63], v[158:161], v[196:199], v[60:63]
	v_mfma_f32_16x16x32_bf16 v[56:59], v[172:175], v[196:199], v[56:59]
	v_mfma_f32_16x16x32_bf16 v[48:51], v[158:161], v[204:207], v[48:51]
	v_mfma_f32_16x16x32_bf16 v[40:43], v[172:175], v[204:207], v[40:43]
	v_mfma_f32_16x16x32_bf16 v[32:35], v[158:161], v[212:215], v[32:35]
	v_mfma_f32_16x16x32_bf16 v[24:27], v[172:175], v[212:215], v[24:27]
	v_mfma_f32_16x16x32_bf16 v[16:19], v[158:161], v[220:223], v[16:19]
	v_mfma_f32_16x16x32_bf16 v[8:11], v[172:175], v[220:223], v[8:11]
	v_mfma_f32_16x16x32_bf16 v[60:63], v[168:171], v[200:203], v[60:63]
	v_mfma_f32_16x16x32_bf16 v[56:59], v[176:179], v[200:203], v[56:59]
	v_mfma_f32_16x16x32_bf16 v[48:51], v[168:171], v[208:211], v[48:51]
	v_mfma_f32_16x16x32_bf16 v[40:43], v[176:179], v[208:211], v[40:43]
	v_mfma_f32_16x16x32_bf16 v[32:35], v[168:171], v[216:219], v[32:35]
	v_mfma_f32_16x16x32_bf16 v[24:27], v[176:179], v[216:219], v[24:27]
	v_mfma_f32_16x16x32_bf16 v[16:19], v[168:171], v[224:227], v[16:19]
	v_mfma_f32_16x16x32_bf16 v[8:11], v[176:179], v[224:227], v[8:11]
	s_setprio 0
	s_setprio 1
	v_mfma_f32_16x16x32_bf16 v[52:55], v[180:183], v[196:199], v[52:55]
	v_mfma_f32_16x16x32_bf16 v[44:47], v[188:191], v[196:199], v[44:47]
	v_mfma_f32_16x16x32_bf16 v[36:39], v[180:183], v[204:207], v[36:39]
	v_mfma_f32_16x16x32_bf16 v[28:31], v[188:191], v[204:207], v[28:31]
	v_mfma_f32_16x16x32_bf16 v[20:23], v[180:183], v[212:215], v[20:23]
	v_mfma_f32_16x16x32_bf16 v[12:15], v[188:191], v[212:215], v[12:15]
	v_mfma_f32_16x16x32_bf16 v[4:7], v[180:183], v[220:223], v[4:7]
	v_mfma_f32_16x16x32_bf16 v[0:3], v[188:191], v[220:223], v[0:3]
	v_mfma_f32_16x16x32_bf16 v[52:55], v[184:187], v[200:203], v[52:55]
	v_mfma_f32_16x16x32_bf16 v[44:47], v[192:195], v[200:203], v[44:47]
	v_mfma_f32_16x16x32_bf16 v[36:39], v[184:187], v[208:211], v[36:39]
	v_mfma_f32_16x16x32_bf16 v[28:31], v[192:195], v[208:211], v[28:31]
	v_mfma_f32_16x16x32_bf16 v[20:23], v[184:187], v[216:219], v[20:23]
	v_mfma_f32_16x16x32_bf16 v[12:15], v[192:195], v[216:219], v[12:15]
	v_mfma_f32_16x16x32_bf16 v[4:7], v[184:187], v[224:227], v[4:7]
	v_mfma_f32_16x16x32_bf16 v[0:3], v[192:195], v[224:227], v[0:3]
	s_setprio 0
	s_barrier
	s_add_i32 s75, 0, 0x18000
	v_add_u32_e32 v146, s75, v150
	v_add_u32_e32 v238, s75, v234
	s_add_i32 s76, 0, 0x1c000
	ds_read_b128 v[158:161], v146
	ds_read_b128 v[168:171], v238
	ds_read_b128 v[172:175], v146 offset:2048
	ds_read_b128 v[176:179], v238 offset:2048
	v_add_u32_e32 v146, s76, v150
	v_add_u32_e32 v238, s76, v234
	ds_read_b128 v[180:183], v146
	ds_read_b128 v[184:187], v238
	ds_read_b128 v[188:191], v146 offset:2048
	ds_read_b128 v[192:195], v238 offset:2048
	s_add_u32 s48, s48, 0x80000
	s_addc_u32 s49, s49, 0
	s_mov_b32 m0, s54
	v_lshl_add_u64 v[232:233], s[48:49], 0, v[136:137]
	ds_read_b128 v[196:199], v154 offset:32768
	ds_read_b128 v[200:203], v237 offset:32768
	ds_read_b128 v[204:207], v154 offset:34816
	ds_read_b128 v[208:211], v237 offset:34816
	ds_read_b128 v[212:215], v154 offset:36864
	ds_read_b128 v[216:219], v237 offset:36864
	ds_read_b128 v[220:223], v154 offset:38912
	ds_read_b128 v[224:227], v237 offset:38912
	global_load_lds_dwordx4 v[232:233], off
	v_lshl_add_u64 v[232:233], s[48:49], 0, v[132:133]
	s_mov_b32 m0, s55
	s_nop 0
	global_load_lds_dwordx4 v[232:233], off
	s_waitcnt vmcnt(8)
	s_waitcnt lgkmcnt(0)
	s_barrier
	s_setprio 1
	s_waitcnt lgkmcnt(0)
	v_mfma_f32_16x16x32_bf16 v[124:127], v[158:161], v[196:199], v[124:127]
	v_mfma_f32_16x16x32_bf16 v[120:123], v[172:175], v[196:199], v[120:123]
	v_mfma_f32_16x16x32_bf16 v[108:111], v[158:161], v[204:207], v[108:111]
	v_mfma_f32_16x16x32_bf16 v[104:107], v[172:175], v[204:207], v[104:107]
	v_mfma_f32_16x16x32_bf16 v[92:95], v[158:161], v[212:215], v[92:95]
	v_mfma_f32_16x16x32_bf16 v[88:91], v[172:175], v[212:215], v[88:91]
	v_mfma_f32_16x16x32_bf16 v[76:79], v[158:161], v[220:223], v[76:79]
	v_mfma_f32_16x16x32_bf16 v[72:75], v[172:175], v[220:223], v[72:75]
	v_mfma_f32_16x16x32_bf16 v[124:127], v[168:171], v[200:203], v[124:127]
	v_mfma_f32_16x16x32_bf16 v[120:123], v[176:179], v[200:203], v[120:123]
	v_mfma_f32_16x16x32_bf16 v[108:111], v[168:171], v[208:211], v[108:111]
	v_mfma_f32_16x16x32_bf16 v[104:107], v[176:179], v[208:211], v[104:107]
	v_mfma_f32_16x16x32_bf16 v[92:95], v[168:171], v[216:219], v[92:95]
	v_mfma_f32_16x16x32_bf16 v[88:91], v[176:179], v[216:219], v[88:91]
	v_mfma_f32_16x16x32_bf16 v[76:79], v[168:171], v[224:227], v[76:79]
	v_mfma_f32_16x16x32_bf16 v[72:75], v[176:179], v[224:227], v[72:75]
	s_setprio 0
	s_setprio 1
	v_mfma_f32_16x16x32_bf16 v[116:119], v[180:183], v[196:199], v[116:119]
	v_mfma_f32_16x16x32_bf16 v[112:115], v[188:191], v[196:199], v[112:115]
	v_mfma_f32_16x16x32_bf16 v[100:103], v[180:183], v[204:207], v[100:103]
	v_mfma_f32_16x16x32_bf16 v[96:99], v[188:191], v[204:207], v[96:99]
	v_mfma_f32_16x16x32_bf16 v[84:87], v[180:183], v[212:215], v[84:87]
	v_mfma_f32_16x16x32_bf16 v[80:83], v[188:191], v[212:215], v[80:83]
	v_mfma_f32_16x16x32_bf16 v[68:71], v[180:183], v[220:223], v[68:71]
	v_mfma_f32_16x16x32_bf16 v[64:67], v[188:191], v[220:223], v[64:67]
	v_mfma_f32_16x16x32_bf16 v[116:119], v[184:187], v[200:203], v[116:119]
	v_mfma_f32_16x16x32_bf16 v[112:115], v[192:195], v[200:203], v[112:115]
	v_mfma_f32_16x16x32_bf16 v[100:103], v[184:187], v[208:211], v[100:103]
	v_mfma_f32_16x16x32_bf16 v[96:99], v[192:195], v[208:211], v[96:99]
	v_mfma_f32_16x16x32_bf16 v[84:87], v[184:187], v[216:219], v[84:87]
	v_mfma_f32_16x16x32_bf16 v[80:83], v[192:195], v[216:219], v[80:83]
	v_mfma_f32_16x16x32_bf16 v[68:71], v[184:187], v[224:227], v[68:71]
	v_mfma_f32_16x16x32_bf16 v[64:67], v[192:195], v[224:227], v[64:67]
	s_setprio 0
	s_barrier
; #define PG8_STAGE(bufoff, gbase, voff) do { _Pragma("unroll") for (int _i = 0; _i < 2; ++_i) \
;         __builtin_amdgcn_global_load_lds((const unsigned*)((const char*)(gbase) + (voff)[_i]), (PG8_LAS unsigned*)(lds + (bufoff) + ldsw + _i * 8192), 16, 0, 0); } while (0)
; #define PG8_LDA(dst, b, h) do { _Pragma("unroll") for (int m = 0; m < 4; ++m) _Pragma("unroll") for (int k = 0; k < 2; ++k) dst[m][k] = *(const PG8_LAS bf16x8*)(lds + PG8_SA(b, h) + aoff + m * 2048 + k * 1024); } while (0)
; #define PG8_MMA(ai, bj, At, Bt) do { __builtin_amdgcn_s_setprio(1); _Pragma("unroll") for (int m = 0; m < 4; ++m) _Pragma("unroll") for (int n = 0; n < 2; ++n) _Pragma("unroll") for (int k = 0; k < 2; ++k) \
;         acc[ai][bj][m][n] = __builtin_amdgcn_mfma_f32_16x16x32_bf16(Bt[n][k], At[m][k], acc[ai][bj][m][n], 0, 0, 0); __builtin_amdgcn_s_setprio(0); } while (0)
; #define PG8_WAIT_V(n) asm volatile("s_waitcnt vmcnt(" #n ")" ::: "memory")
; #define PG8_WAIT_L(n) asm volatile("s_waitcnt lgkmcnt(" #n ")" ::: "memory")
; #define PG8_BAR __builtin_amdgcn_s_barrier()
; #define PG8_SCHED __builtin_amdgcn_sched_barrier(0)
; template <class Epi, class Sched, bool ALIGN_EPI = false, bool SP2 = false>
; __device__ __forceinline__ void gemm_phase(PG8_LAS unsigned char* lds, const Gemm g, const Sched& S, const Epi& E) {
;     ...
;             PG8_LDA(At, 1, 1); PG8_STAGE(PG8_SB(1, 0), b3, voffB); PG8_STAGE(PG8_SB(1, 1), b3 + hstep, voffB); PG8_STAGE(PG8_SA(1, 0), a3, voffA);
;             PG8_WAIT_V(8); PG8_WAIT_L(0); PG8_BAR; PG8_MMA(1, 0, At, B0); PG8_MMA(1, 1, At, B1); PG8_BAR; PG8_SCHED;
	s_add_i32 s48, s75, s50
	v_lshl_add_u64 v[148:149], v[148:149], 0, s[10:11]
	s_mov_b32 m0, s48
	ds_read_b128 v[196:199], v154 offset:49152
	ds_read_b128 v[200:203], v237 offset:49152
	ds_read_b128 v[204:207], v154 offset:51200
	ds_read_b128 v[208:211], v237 offset:51200
	ds_read_b128 v[212:215], v154 offset:53248
	ds_read_b128 v[216:219], v237 offset:53248
	ds_read_b128 v[220:223], v154 offset:55296
	ds_read_b128 v[224:227], v237 offset:55296
	global_load_lds_dwordx4 v[148:149], off
	s_add_i32 m0, s48, 0x2000
	s_add_u32 s46, s46, 0x80080
	v_lshl_add_u64 v[148:149], v[162:163], 0, s[10:11]
	s_addc_u32 s47, s47, 0
	s_add_i32 s48, s76, s50
	global_load_lds_dwordx4 v[148:149], off
	v_lshl_add_u64 v[148:149], s[46:47], 0, v[134:135]
	s_mov_b32 m0, s48
	s_nop 0
	global_load_lds_dwordx4 v[148:149], off
	v_lshl_add_u64 v[148:149], s[46:47], 0, v[130:131]
	s_add_i32 m0, s48, 0x2000
	s_nop 0
	global_load_lds_dwordx4 v[148:149], off
	v_lshl_add_u64 v[148:149], v[228:229], 0, s[10:11]
	s_mov_b32 m0, s59
	s_nop 0
	global_load_lds_dwordx4 v[148:149], off
	v_lshl_add_u64 v[148:149], v[230:231], 0, s[10:11]
	s_mov_b32 m0, s60
	s_nop 0
	global_load_lds_dwordx4 v[148:149], off
	s_waitcnt vmcnt(8)
	s_waitcnt lgkmcnt(0)
	s_barrier
	s_setprio 1
	s_waitcnt lgkmcnt(0)
	v_mfma_f32_16x16x32_bf16 v[60:63], v[158:161], v[196:199], v[60:63]
	v_mfma_f32_16x16x32_bf16 v[56:59], v[172:175], v[196:199], v[56:59]
	v_mfma_f32_16x16x32_bf16 v[48:51], v[158:161], v[204:207], v[48:51]
	v_mfma_f32_16x16x32_bf16 v[40:43], v[172:175], v[204:207], v[40:43]
	v_mfma_f32_16x16x32_bf16 v[32:35], v[158:161], v[212:215], v[32:35]
	v_mfma_f32_16x16x32_bf16 v[24:27], v[172:175], v[212:215], v[24:27]
	v_mfma_f32_16x16x32_bf16 v[16:19], v[158:161], v[220:223], v[16:19]
	v_mfma_f32_16x16x32_bf16 v[8:11], v[172:175], v[220:223], v[8:11]
	v_mfma_f32_16x16x32_bf16 v[60:63], v[168:171], v[200:203], v[60:63]
	v_mfma_f32_16x16x32_bf16 v[56:59], v[176:179], v[200:203], v[56:59]
	v_mfma_f32_16x16x32_bf16 v[48:51], v[168:171], v[208:211], v[48:51]
	v_mfma_f32_16x16x32_bf16 v[40:43], v[176:179], v[208:211], v[40:43]
	v_mfma_f32_16x16x32_bf16 v[32:35], v[168:171], v[216:219], v[32:35]
	v_mfma_f32_16x16x32_bf16 v[24:27], v[176:179], v[216:219], v[24:27]
	v_mfma_f32_16x16x32_bf16 v[16:19], v[168:171], v[224:227], v[16:19]
	v_mfma_f32_16x16x32_bf16 v[8:11], v[176:179], v[224:227], v[8:11]
	s_setprio 0
	s_setprio 1
	v_mfma_f32_16x16x32_bf16 v[52:55], v[180:183], v[196:199], v[52:55]
	v_mfma_f32_16x16x32_bf16 v[44:47], v[188:191], v[196:199], v[44:47]
	v_mfma_f32_16x16x32_bf16 v[36:39], v[180:183], v[204:207], v[36:39]
	v_mfma_f32_16x16x32_bf16 v[28:31], v[188:191], v[204:207], v[28:31]
	v_mfma_f32_16x16x32_bf16 v[20:23], v[180:183], v[212:215], v[20:23]
	v_mfma_f32_16x16x32_bf16 v[12:15], v[188:191], v[212:215], v[12:15]
	v_mfma_f32_16x16x32_bf16 v[4:7], v[180:183], v[220:223], v[4:7]
	v_mfma_f32_16x16x32_bf16 v[0:3], v[188:191], v[220:223], v[0:3]
	v_mfma_f32_16x16x32_bf16 v[52:55], v[184:187], v[200:203], v[52:55]
	v_mfma_f32_16x16x32_bf16 v[44:47], v[192:195], v[200:203], v[44:47]
	v_mfma_f32_16x16x32_bf16 v[36:39], v[184:187], v[208:211], v[36:39]
	v_mfma_f32_16x16x32_bf16 v[28:31], v[192:195], v[208:211], v[28:31]
	v_mfma_f32_16x16x32_bf16 v[20:23], v[184:187], v[216:219], v[20:23]
	v_mfma_f32_16x16x32_bf16 v[12:15], v[192:195], v[216:219], v[12:15]
	v_mfma_f32_16x16x32_bf16 v[4:7], v[184:187], v[224:227], v[4:7]
	v_mfma_f32_16x16x32_bf16 v[0:3], v[192:195], v[224:227], v[0:3]
	s_setprio 0
	s_barrier
	s_add_i32 s74, s74, 2
	s_add_u32 s6, s6, 0x100
	s_addc_u32 s7, s7, 0
	s_add_u32 s72, s72, 0x100
	s_addc_u32 s73, s73, 0
	s_cmp_gt_u32 s74, 29
	s_cbranch_scc0 .LBB0_99
	s_and_b64 vcc, exec, s[18:19]
	s_cbranch_vccz .LBB0_102
	s_barrier

; __global__ void __launch_bounds__(NWAVES * 64, 2) mk_fwd(Args a_unused) {
	.amdhsa_kernel _Z6mk_fwd4Args
		.amdhsa_group_segment_fixed_size 0
		.amdhsa_private_segment_fixed_size 0
		.amdhsa_kernarg_size 416
		.amdhsa_user_sgpr_count 2
		.amdhsa_user_sgpr_dispatch_ptr 0
		.amdhsa_user_sgpr_queue_ptr 0
		.amdhsa_user_sgpr_kernarg_segment_ptr 1
		.amdhsa_user_sgpr_dispatch_id 0
		.amdhsa_user_sgpr_kernarg_preload_length 0
		.amdhsa_user_sgpr_kernarg_preload_offset 0
		.amdhsa_user_sgpr_private_segment_size 0
		.amdhsa_uses_dynamic_stack 0
		.amdhsa_enable_private_segment 0
		.amdhsa_system_sgpr_workgroup_id_x 1
		.amdhsa_system_sgpr_workgroup_id_y 0
		.amdhsa_system_sgpr_workgroup_id_z 0
		.amdhsa_system_sgpr_workgroup_info 0
		.amdhsa_system_vgpr_workitem_id 2
		.amdhsa_next_free_vgpr 256
		.amdhsa_next_free_sgpr 98
		.amdhsa_accum_offset 256
		.amdhsa_reserve_vcc 1
		.amdhsa_float_round_mode_32 0
		.amdhsa_float_round_mode_16_64 0
		.amdhsa_float_denorm_mode_32 3
		.amdhsa_float_denorm_mode_16_64 3
		.amdhsa_dx10_clamp 1
		.amdhsa_ieee_mode 1
		.amdhsa_fp16_overflow 0
		.amdhsa_tg_split 0
		.amdhsa_exception_fp_ieee_invalid_op 0
		.amdhsa_exception_fp_denorm_src 0
		.amdhsa_exception_fp_ieee_div_zero 0
		.amdhsa_exception_fp_ieee_overflow 0
		.amdhsa_exception_fp_ieee_underflow 0
		.amdhsa_exception_fp_ieee_inexact 0
		.amdhsa_exception_int_div_zero 0
	.end_amdhsa_kernel

; __global__ void __launch_bounds__(NWAVES * 64, 2) mk_fwd(Args a_unused) {
amdhsa.kernels:
  - .agpr_count:     0
    .args:
      - .offset:         0
        .size:           160
        .value_kind:     by_value
      - .offset:         160
        .size:           4
        .value_kind:     hidden_block_count_x
      - .offset:         164
        .size:           4
        .value_kind:     hidden_block_count_y
      - .offset:         168
        .size:           4
        .value_kind:     hidden_block_count_z
      - .offset:         172
        .size:           2
        .value_kind:     hidden_group_size_x
      - .offset:         174
        .size:           2
        .value_kind:     hidden_group_size_y
      - .offset:         176
        .size:           2
        .value_kind:     hidden_group_size_z
      - .offset:         178
        .size:           2
        .value_kind:     hidden_remainder_x
      - .offset:         180
        .size:           2
        .value_kind:     hidden_remainder_y
      - .offset:         182
        .size:           2
        .value_kind:     hidden_remainder_z
      - .offset:         200
        .size:           8
        .value_kind:     hidden_global_offset_x
      - .offset:         208
        .size:           8
        .value_kind:     hidden_global_offset_y
      - .offset:         216
        .size:           8
        .value_kind:     hidden_global_offset_z
      - .offset:         224
        .size:           2
        .value_kind:     hidden_grid_dims
      - .offset:         248
        .size:           8
        .value_kind:     hidden_multigrid_sync_arg
      - .offset:         280
        .size:           4
        .value_kind:     hidden_dynamic_lds_size
    .group_segment_fixed_size: 0
    .kernarg_segment_align: 8
    .kernarg_segment_size: 416
    .language:       OpenCL C
    .language_version:
      - 2
      - 0
    .max_flat_workgroup_size: 512
    .name:           _Z6mk_fwd4Args
    .private_segment_fixed_size: 0
    .sgpr_count:     104
    .sgpr_spill_count: 0
    .symbol:         _Z6mk_fwd4Args.kd
    .uniform_work_group_size: 1
    .uses_dynamic_stack: false
    .vgpr_count:     256
    .vgpr_spill_count: 0
    .wavefront_size: 64
